# A1: the vmcnt(0) drain between the two selects (guarding a pending weight load) moved to the score-loop exit, so the bm store latency is no longer exposed
# baseline (speedup 1.0000x reference)
; DI void a1_select(const Params& p, const float* scrow, int t, size_t tokrow, int lane) {
;     ...
;   } else {
; #pragma unroll
;     for (int i = 0; i < 32; ++i) {
;       const unsigned long long sb = __ballot(i * 64 + lane <= t);
;       if (lane == i) myword = sb;
;     }
; DI void phaseA1(const Params& p, int vblock, int nvblocks, int ubegin, int uend, char* smem) {
;     ...
;     __syncthreads();
;     a1_select(p, sc + wid * 2048, q0 + wid, tokb + q0 + wid, lane);
.LBB0_352:
	s_or_b64 exec, exec, s[84:85]
	s_waitcnt vmcnt(0)
	v_add_u32_e32 v2, s88, v98
	v_cmp_gt_i32_e32 vcc, s42, v2
	v_sub_u32_e32 v2, v2, v103
	s_waitcnt lgkmcnt(0)
	s_barrier
	s_and_saveexec_b64 s[2:3], vcc
	v_readlane_b32 s44, v253, 61
	s_xor_b64 s[2:3], exec, s[2:3]
	s_movk_i32 s37, 0x80
	v_readlane_b32 s45, v253, 62
	s_movk_i32 s43, 0xfff
	s_movk_i32 s46, 0x7fff
	s_mov_b32 s47, 0xfffffc0
	s_mov_b64 s[48:49], 0x8000
	s_mov_b32 s51, 0x8000
	s_cbranch_execz .LBB0_354
	v_cmp_lt_i32_e32 vcc, -1, v2
	s_movk_i32 s14, 0xbf
	s_nop 0
	v_mov_b32_e32 v3, vcc_hi
	v_mov_b32_e32 v4, vcc_lo
	v_cmp_lt_i32_e32 vcc, 63, v2
	v_cndmask_b32_e64 v4, 0, v4, s[0:1]
	v_cndmask_b32_e64 v3, 0, v3, s[0:1]
	v_mov_b32_e32 v5, vcc_lo
	v_cndmask_b32_e64 v4, v4, v5, s[4:5]
	v_mov_b32_e32 v5, vcc_hi
	v_cmp_lt_i32_e32 vcc, s33, v2
	v_cndmask_b32_e64 v3, v3, v5, s[4:5]
	s_nop 0
	v_mov_b32_e32 v5, vcc_hi
	v_cndmask_b32_e64 v3, v3, v5, s[6:7]
	v_mov_b32_e32 v5, vcc_lo
	v_cmp_lt_i32_e32 vcc, s14, v2
	v_cndmask_b32_e64 v4, v4, v5, s[6:7]
	s_nop 0
	v_mov_b32_e32 v2, vcc_lo
	v_cndmask_b32_e64 v2, v4, v2, s[8:9]
	v_mov_b32_e32 v4, vcc_hi
	v_cndmask_b32_e64 v3, v3, v4, s[8:9]
	v_cndmask_b32_e64 v5, v3, 0, s[58:59]
	v_cndmask_b32_e64 v4, v2, 0, s[58:59]

; DI void a1_select(const Params& p, const float* scrow, int t, size_t tokrow, int lane) {
;     ...
;   } else {
; #pragma unroll
;     for (int i = 0; i < 32; ++i) {
;       const unsigned long long sb = __ballot(i * 64 + lane <= t);
;       if (lane == i) myword = sb;
;     }
; DI void phaseA1(const Params& p, int vblock, int nvblocks, int ubegin, int uend, char* smem) {
;     ...
;     a1_select(p, sc + wid * 2048, q0 + wid, tokb + q0 + wid, lane);
;     a1_select(p, sc + (4 + wid) * 2048, q0 + 4 + wid, tokb + q0 + 4 + wid, lane);
.LBB0_564:
	s_or_b64 exec, exec, s[2:3]
	v_add3_u32 v4, v98, s88, 4
	v_cmp_gt_i32_e32 vcc, s42, v4
	v_sub_u32_e32 v6, v4, v103
	s_and_saveexec_b64 s[2:3], vcc
	s_xor_b64 s[2:3], exec, s[2:3]
	s_cbranch_execz .LBB0_566
	v_cmp_lt_i32_e32 vcc, -1, v6
	s_movk_i32 s12, 0xbf
	s_nop 0
	v_mov_b32_e32 v4, vcc_hi
	v_mov_b32_e32 v5, vcc_lo
	v_cmp_lt_i32_e32 vcc, 63, v6
	v_cndmask_b32_e64 v5, 0, v5, s[0:1]
	v_cndmask_b32_e64 v4, 0, v4, s[0:1]
	v_mov_b32_e32 v7, vcc_lo
	v_cndmask_b32_e64 v5, v5, v7, s[4:5]
	v_mov_b32_e32 v7, vcc_hi
	v_cmp_lt_i32_e32 vcc, s33, v6
	v_cndmask_b32_e64 v4, v4, v7, s[4:5]
	s_nop 0
	v_mov_b32_e32 v7, vcc_hi
	v_cndmask_b32_e64 v4, v4, v7, s[6:7]
	v_mov_b32_e32 v7, vcc_lo
	v_cmp_lt_i32_e32 vcc, s12, v6
	v_cndmask_b32_e64 v5, v5, v7, s[6:7]
	s_nop 0
	v_mov_b32_e32 v6, vcc_lo
	v_cndmask_b32_e64 v6, v5, v6, s[8:9]
	v_mov_b32_e32 v5, vcc_hi
	v_cndmask_b32_e64 v4, v4, v5, s[8:9]
	v_cndmask_b32_e64 v5, v4, 0, s[58:59]
	v_cndmask_b32_e64 v4, v6, 0, s[58:59]

; DI void a1_select(const Params& p, const float* scrow, int t, size_t tokrow, int lane) {
;     ...
;   } else {
; #pragma unroll
;     for (int i = 0; i < 32; ++i) {
;       const unsigned long long sb = __ballot(i * 64 + lane <= t);
;       if (lane == i) myword = sb;
;     }
; DI void phaseA1(const Params& p, int vblock, int nvblocks, int ubegin, int uend, char* smem) {
;     ...
;     __syncthreads();
;     a1_select(p, sc + wid * 2048, q0 + wid, tokb + q0 + wid, lane);
.LBB0_811:
	s_or_b64 exec, exec, s[84:85]
	s_waitcnt vmcnt(0)
	v_add_u32_e32 v2, s88, v98
	v_cmp_gt_i32_e32 vcc, s42, v2
	v_sub_u32_e32 v2, v2, v103
	s_waitcnt lgkmcnt(0)
	s_barrier
	s_and_saveexec_b64 s[2:3], vcc
	s_xor_b64 s[2:3], exec, s[2:3]
	s_cbranch_execz .LBB0_813
	v_cmp_lt_i32_e32 vcc, -1, v2
	s_movk_i32 s14, 0xbf
	s_nop 0
	v_mov_b32_e32 v3, vcc_hi
	v_mov_b32_e32 v4, vcc_lo
	v_cmp_lt_i32_e32 vcc, 63, v2
	v_cndmask_b32_e64 v4, 0, v4, s[0:1]
	v_cndmask_b32_e64 v3, 0, v3, s[0:1]
	v_mov_b32_e32 v5, vcc_lo
	v_cndmask_b32_e64 v4, v4, v5, s[4:5]
	v_mov_b32_e32 v5, vcc_hi
	v_cmp_lt_i32_e32 vcc, s33, v2
	v_cndmask_b32_e64 v3, v3, v5, s[4:5]
	s_nop 0
	v_mov_b32_e32 v5, vcc_hi
	v_cndmask_b32_e64 v3, v3, v5, s[6:7]
	v_mov_b32_e32 v5, vcc_lo
	v_cmp_lt_i32_e32 vcc, s14, v2
	v_cndmask_b32_e64 v4, v4, v5, s[6:7]
	s_nop 0
	v_mov_b32_e32 v2, vcc_lo
	v_cndmask_b32_e64 v2, v4, v2, s[8:9]
	v_mov_b32_e32 v4, vcc_hi
	v_cndmask_b32_e64 v3, v3, v4, s[8:9]
	v_cndmask_b32_e64 v5, v3, 0, s[58:59]
	v_cndmask_b32_e64 v4, v2, 0, s[58:59]

; DI void a1_select(const Params& p, const float* scrow, int t, size_t tokrow, int lane) {
;     ...
;   } else {
; #pragma unroll
;     for (int i = 0; i < 32; ++i) {
;       const unsigned long long sb = __ballot(i * 64 + lane <= t);
;       if (lane == i) myword = sb;
;     }
; DI void phaseA1(const Params& p, int vblock, int nvblocks, int ubegin, int uend, char* smem) {
;     ...
;     __syncthreads();
;     a1_select(p, sc + wid * 2048, q0 + wid, tokb + q0 + wid, lane);
.LBB0_1329:
	s_or_b64 exec, exec, s[84:85]
	s_waitcnt vmcnt(0)
	v_add_u32_e32 v2, s88, v98
	v_cmp_gt_i32_e32 vcc, s42, v2
	v_sub_u32_e32 v2, v2, v103
	s_waitcnt lgkmcnt(0)
	s_barrier
	s_and_saveexec_b64 s[2:3], vcc
	s_xor_b64 s[2:3], exec, s[2:3]
	s_cbranch_execz .LBB0_1331
	v_cmp_lt_i32_e32 vcc, -1, v2
	s_movk_i32 s14, 0xbf
	s_nop 0
	v_mov_b32_e32 v3, vcc_hi
	v_mov_b32_e32 v4, vcc_lo
	v_cmp_lt_i32_e32 vcc, 63, v2
	v_cndmask_b32_e64 v4, 0, v4, s[0:1]
	v_cndmask_b32_e64 v3, 0, v3, s[0:1]
	v_mov_b32_e32 v5, vcc_lo
	v_cndmask_b32_e64 v4, v4, v5, s[4:5]
	v_mov_b32_e32 v5, vcc_hi
	v_cmp_lt_i32_e32 vcc, s33, v2
	v_cndmask_b32_e64 v3, v3, v5, s[4:5]
	s_nop 0
	v_mov_b32_e32 v5, vcc_hi
	v_cndmask_b32_e64 v3, v3, v5, s[6:7]
	v_mov_b32_e32 v5, vcc_lo
	v_cmp_lt_i32_e32 vcc, s14, v2
	v_cndmask_b32_e64 v4, v4, v5, s[6:7]
	s_nop 0
	v_mov_b32_e32 v2, vcc_lo
	v_cndmask_b32_e64 v2, v4, v2, s[8:9]
	v_mov_b32_e32 v4, vcc_hi
	v_cndmask_b32_e64 v3, v3, v4, s[8:9]
	v_cndmask_b32_e64 v5, v3, 0, s[62:63]
	v_cndmask_b32_e64 v4, v2, 0, s[62:63]

; DI void a1_select(const Params& p, const float* scrow, int t, size_t tokrow, int lane) {
;     ...
;   } else {
; #pragma unroll
;     for (int i = 0; i < 32; ++i) {
;       const unsigned long long sb = __ballot(i * 64 + lane <= t);
;       if (lane == i) myword = sb;
;     }
; DI void phaseA1(const Params& p, int vblock, int nvblocks, int ubegin, int uend, char* smem) {
;     ...
;     a1_select(p, sc + wid * 2048, q0 + wid, tokb + q0 + wid, lane);
;     a1_select(p, sc + (4 + wid) * 2048, q0 + 4 + wid, tokb + q0 + 4 + wid, lane);
.LBB0_1541:
	s_or_b64 exec, exec, s[2:3]
	v_add3_u32 v4, v98, s88, 4
	v_cmp_gt_i32_e32 vcc, s42, v4
	v_sub_u32_e32 v6, v4, v103
	s_and_saveexec_b64 s[2:3], vcc
	s_xor_b64 s[2:3], exec, s[2:3]
	s_cbranch_execz .LBB0_1543
	v_cmp_lt_i32_e32 vcc, -1, v6
	s_movk_i32 s12, 0xbf
	s_nop 0
	v_mov_b32_e32 v4, vcc_hi
	v_mov_b32_e32 v5, vcc_lo
	v_cmp_lt_i32_e32 vcc, 63, v6
	v_cndmask_b32_e64 v5, 0, v5, s[0:1]
	v_cndmask_b32_e64 v4, 0, v4, s[0:1]
	v_mov_b32_e32 v7, vcc_lo
	v_cndmask_b32_e64 v5, v5, v7, s[4:5]
	v_mov_b32_e32 v7, vcc_hi
	v_cmp_lt_i32_e32 vcc, s33, v6
	v_cndmask_b32_e64 v4, v4, v7, s[4:5]
	s_nop 0
	v_mov_b32_e32 v7, vcc_hi
	v_cndmask_b32_e64 v4, v4, v7, s[6:7]
	v_mov_b32_e32 v7, vcc_lo
	v_cmp_lt_i32_e32 vcc, s12, v6
	v_cndmask_b32_e64 v5, v5, v7, s[6:7]
	s_nop 0
	v_mov_b32_e32 v6, vcc_lo
	v_cndmask_b32_e64 v6, v5, v6, s[8:9]
	v_mov_b32_e32 v5, vcc_hi
	v_cndmask_b32_e64 v4, v4, v5, s[8:9]
	v_cndmask_b32_e64 v5, v4, 0, s[62:63]
	v_cndmask_b32_e64 v4, v6, 0, s[62:63]
